# attention compute block hand-interleaved (MFMA/VALU/LDS) + w_up transpose loads batched (48 in flight instead of 1)
# speedup vs baseline: 1.2817x; 1.2817x over previous
.LBB0_548:
	s_cmp_gt_u32 s52, s51
	s_mul_i32 s61, s25, 0x2200
	s_cbranch_scc1 .LBB0_550
	s_and_b32 s42, s52, 2
	s_mulk_i32 s42, 0x3400
	v_add_u32_e32 v0, s42, v160
	v_add_u32_e32 v242, s61, v161
	v_add_u32_e32 v163, 0xe000, v242
	v_add_u32_e32 v242, 0xd000, v242
	ds_read_b128 v[82:85], v0 offset:13312
	ds_read_b128 v[98:101], v0 offset:19968
	ds_read_b128 v[164:167], v0 offset:13344
	ds_read_b128 v[168:171], v0 offset:20000
	ds_read2_b64 v[238:241], v242 offset0:0 offset1:2
	ds_read2_b64 v[234:237], v163 offset0:32 offset1:34
	ds_read_b128 v[172:175], v0 offset:13376
	ds_read_b128 v[176:179], v0 offset:20032
	ds_read_b128 v[180:183], v0 offset:13408
	ds_read_b128 v[184:187], v0 offset:20064
	ds_read_b128 v[188:191], v0 offset:13440
	ds_read_b128 v[192:195], v0 offset:20096
	ds_read_b128 v[196:199], v0 offset:13472
	ds_read_b128 v[220:223], v0 offset:20128
	v_exp_f32_e32 v50, v50
	v_exp_f32_e32 v51, v51
	v_exp_f32_e32 v52, v52
	v_exp_f32_e32 v53, v53
	v_exp_f32_e32 v54, v54
	v_exp_f32_e32 v55, v55
	v_exp_f32_e32 v56, v56
	v_exp_f32_e32 v57, v57
	s_waitcnt lgkmcnt(13)
	v_mfma_f32_32x32x16_bf16 v[82:97], v[82:85], v[122:125], 0
	v_cvt_pk_bf16_f32 v224, v50, v51
	v_cvt_pk_bf16_f32 v225, v52, v53
	v_cvt_pk_bf16_f32 v226, v54, v55
	v_cvt_pk_bf16_f32 v227, v56, v57
	v_exp_f32_e32 v58, v58
	v_add_f32_e32 v200, v50, v51
	s_waitcnt lgkmcnt(12)
	v_mfma_f32_32x32x16_bf16 v[98:113], v[98:101], v[122:125], 0
	v_exp_f32_e32 v59, v59
	v_exp_f32_e32 v60, v60
	v_add_f32_e32 v201, v52, v53
	v_exp_f32_e32 v61, v61
	s_waitcnt lgkmcnt(11)
	v_mfma_f32_32x32x16_bf16 v[82:97], v[164:167], v[126:129], v[82:97]
	v_exp_f32_e32 v62, v62
	v_add_f32_e32 v200, v200, v54
	v_exp_f32_e32 v63, v63
	v_add_f32_e32 v201, v201, v55
	v_exp_f32_e32 v64, v64
	s_waitcnt lgkmcnt(10)
	v_mfma_f32_32x32x16_bf16 v[98:113], v[168:171], v[126:129], v[98:113]
	ds_read2_b64 v[164:167], v242 offset0:4 offset1:6
	ds_read2_b64 v[168:171], v163 offset0:36 offset1:38
	v_add_f32_e32 v200, v200, v56
	v_exp_f32_e32 v65, v65
	v_add_f32_e32 v201, v201, v57
	v_cvt_pk_bf16_f32 v228, v58, v59
	v_cvt_pk_bf16_f32 v229, v60, v61
	s_waitcnt lgkmcnt(11)
	v_mfma_f32_32x32x16_bf16 v[18:33], v[238:241], v[224:227], v[18:33]
	v_cvt_pk_bf16_f32 v230, v62, v63
	v_cvt_pk_bf16_f32 v231, v64, v65
	v_exp_f32_e32 v66, v66
	v_add_f32_e32 v200, v200, v58
	v_exp_f32_e32 v67, v67
	v_add_f32_e32 v201, v201, v59
	s_waitcnt lgkmcnt(10)
	v_mfma_f32_32x32x16_bf16 v[34:49], v[234:237], v[224:227], v[34:49]
	v_exp_f32_e32 v68, v68
	v_add_f32_e32 v200, v200, v60
	v_exp_f32_e32 v69, v69
	v_add_f32_e32 v201, v201, v61
	v_exp_f32_e32 v70, v70
	s_waitcnt lgkmcnt(9)
	v_mfma_f32_32x32x16_bf16 v[82:97], v[172:175], v[134:137], v[82:97]
	v_add_f32_e32 v200, v200, v62
	v_exp_f32_e32 v71, v71
	v_add_f32_e32 v201, v201, v63
	v_exp_f32_e32 v72, v72
	v_add_f32_e32 v200, v200, v64
	s_waitcnt lgkmcnt(8)
	v_mfma_f32_32x32x16_bf16 v[98:113], v[176:179], v[134:137], v[98:113]
	ds_read2_b64 v[172:175], v242 offset0:8 offset1:10
	ds_read2_b64 v[176:179], v163 offset0:40 offset1:42
	v_exp_f32_e32 v73, v73
	v_add_f32_e32 v201, v201, v65
	v_cvt_pk_bf16_f32 v224, v66, v67
	v_cvt_pk_bf16_f32 v225, v68, v69
	v_cvt_pk_bf16_f32 v226, v70, v71
	s_waitcnt lgkmcnt(3)
	v_mfma_f32_32x32x16_bf16 v[18:33], v[164:167], v[228:231], v[18:33]
	v_cvt_pk_bf16_f32 v227, v72, v73
	v_exp_f32_e32 v74, v74
	v_add_f32_e32 v200, v200, v66
	v_exp_f32_e32 v75, v75
	v_add_f32_e32 v201, v201, v67
	s_waitcnt lgkmcnt(2)
	v_mfma_f32_32x32x16_bf16 v[34:49], v[168:171], v[228:231], v[34:49]
	v_exp_f32_e32 v76, v76
	v_add_f32_e32 v200, v200, v68
	v_exp_f32_e32 v77, v77
	v_add_f32_e32 v201, v201, v69
	v_exp_f32_e32 v78, v78
	s_waitcnt lgkmcnt(9)
	v_mfma_f32_32x32x16_bf16 v[82:97], v[180:183], v[138:141], v[82:97]
	v_add_f32_e32 v200, v200, v70
	v_exp_f32_e32 v79, v79
	v_add_f32_e32 v201, v201, v71
	v_exp_f32_e32 v80, v80
	v_add_f32_e32 v200, v200, v72
	s_waitcnt lgkmcnt(8)
	v_mfma_f32_32x32x16_bf16 v[98:113], v[184:187], v[138:141], v[98:113]
	ds_read2_b64 v[180:183], v242 offset0:12 offset1:14
	ds_read2_b64 v[184:187], v163 offset0:44 offset1:46
	v_exp_f32_e32 v81, v81
	v_add_f32_e32 v201, v201, v73
	v_cvt_pk_bf16_f32 v228, v74, v75
	v_cvt_pk_bf16_f32 v229, v76, v77
	v_cvt_pk_bf16_f32 v230, v78, v79
	s_waitcnt lgkmcnt(3)
	v_mfma_f32_32x32x16_bf16 v[18:33], v[172:175], v[224:227], v[18:33]
	v_cvt_pk_bf16_f32 v231, v80, v81
	v_add_f32_e32 v200, v200, v74
	v_add_f32_e32 v201, v201, v75
	v_add_f32_e32 v200, v200, v76
	v_add_f32_e32 v201, v201, v77
	v_add_f32_e32 v200, v200, v78
	v_add_f32_e32 v201, v201, v79
	v_add_f32_e32 v200, v200, v80
	s_waitcnt lgkmcnt(2)
	v_mfma_f32_32x32x16_bf16 v[34:49], v[176:179], v[224:227], v[34:49]
	v_add_f32_e32 v201, v201, v81
	v_add_f32_e32 v200, v200, v201
	v_add_f32_e32 v162, v162, v200
	s_waitcnt lgkmcnt(9)
	v_mfma_f32_32x32x16_bf16 v[82:97], v[188:191], v[142:145], v[82:97]
	s_waitcnt lgkmcnt(8)
	v_mfma_f32_32x32x16_bf16 v[98:113], v[192:195], v[142:145], v[98:113]
	s_waitcnt lgkmcnt(7)
	v_mfma_f32_32x32x16_bf16 v[82:97], v[196:199], v[146:149], v[82:97]
	s_waitcnt lgkmcnt(6)
	v_mfma_f32_32x32x16_bf16 v[98:113], v[220:223], v[146:149], v[98:113]
	s_waitcnt lgkmcnt(1)
	v_mfma_f32_32x32x16_bf16 v[18:33], v[180:183], v[228:231], v[18:33]
	s_waitcnt lgkmcnt(0)
	v_mfma_f32_32x32x16_bf16 v[34:49], v[184:187], v[228:231], v[34:49]

.LBB0_563:
	s_cmp_ge_u32 s52, s51
	s_mul_i32 s58, s25, 0x2200
	s_cbranch_scc1 .LBB0_565
	s_andn2_b32 s52, 2, s52
	s_mulk_i32 s52, 0x3400
	v_add_u32_e32 v0, s52, v160
	v_add_u32_e32 v242, s58, v161
	v_add_u32_e32 v163, 0xe000, v242
	v_add_u32_e32 v242, 0xd000, v242
	ds_read_b128 v[50:53], v0 offset:0
	ds_read_b128 v[66:69], v0 offset:6656
	ds_read_b128 v[164:167], v0 offset:32
	ds_read_b128 v[168:171], v0 offset:6688
	ds_read2_b64 v[238:241], v242 offset0:0 offset1:2
	ds_read2_b64 v[234:237], v163 offset0:32 offset1:34
	ds_read_b128 v[172:175], v0 offset:64
	ds_read_b128 v[176:179], v0 offset:6720
	ds_read_b128 v[180:183], v0 offset:96
	ds_read_b128 v[184:187], v0 offset:6752
	ds_read_b128 v[188:191], v0 offset:128
	ds_read_b128 v[192:195], v0 offset:6784
	ds_read_b128 v[196:199], v0 offset:160
	ds_read_b128 v[220:223], v0 offset:6816
	v_exp_f32_e32 v82, v82
	v_exp_f32_e32 v83, v83
	v_exp_f32_e32 v84, v84
	v_exp_f32_e32 v85, v85
	v_exp_f32_e32 v86, v86
	v_exp_f32_e32 v87, v87
	v_exp_f32_e32 v88, v88
	v_exp_f32_e32 v89, v89
	s_waitcnt lgkmcnt(13)
	v_mfma_f32_32x32x16_bf16 v[50:65], v[50:53], v[122:125], 0
	v_cvt_pk_bf16_f32 v224, v82, v83
	v_cvt_pk_bf16_f32 v225, v84, v85
	v_cvt_pk_bf16_f32 v226, v86, v87
	v_cvt_pk_bf16_f32 v227, v88, v89
	v_exp_f32_e32 v90, v90
	v_add_f32_e32 v200, v82, v83
	s_waitcnt lgkmcnt(12)
	v_mfma_f32_32x32x16_bf16 v[66:81], v[66:69], v[122:125], 0
	v_exp_f32_e32 v91, v91
	v_exp_f32_e32 v92, v92
	v_add_f32_e32 v201, v84, v85
	v_exp_f32_e32 v93, v93
	s_waitcnt lgkmcnt(11)
	v_mfma_f32_32x32x16_bf16 v[50:65], v[164:167], v[126:129], v[50:65]
	v_exp_f32_e32 v94, v94
	v_add_f32_e32 v200, v200, v86
	v_exp_f32_e32 v95, v95
	v_add_f32_e32 v201, v201, v87
	v_exp_f32_e32 v96, v96
	s_waitcnt lgkmcnt(10)
	v_mfma_f32_32x32x16_bf16 v[66:81], v[168:171], v[126:129], v[66:81]
	ds_read2_b64 v[164:167], v242 offset0:4 offset1:6
	ds_read2_b64 v[168:171], v163 offset0:36 offset1:38
	v_add_f32_e32 v200, v200, v88
	v_exp_f32_e32 v97, v97
	v_add_f32_e32 v201, v201, v89
	v_cvt_pk_bf16_f32 v228, v90, v91
	v_cvt_pk_bf16_f32 v229, v92, v93
	s_waitcnt lgkmcnt(11)
	v_mfma_f32_32x32x16_bf16 v[18:33], v[238:241], v[224:227], v[18:33]
	v_cvt_pk_bf16_f32 v230, v94, v95
	v_cvt_pk_bf16_f32 v231, v96, v97
	v_exp_f32_e32 v98, v98
	v_add_f32_e32 v200, v200, v90
	v_exp_f32_e32 v99, v99
	v_add_f32_e32 v201, v201, v91
	s_waitcnt lgkmcnt(10)
	v_mfma_f32_32x32x16_bf16 v[34:49], v[234:237], v[224:227], v[34:49]
	v_exp_f32_e32 v100, v100
	v_add_f32_e32 v200, v200, v92
	v_exp_f32_e32 v101, v101
	v_add_f32_e32 v201, v201, v93
	v_exp_f32_e32 v102, v102
	s_waitcnt lgkmcnt(9)
	v_mfma_f32_32x32x16_bf16 v[50:65], v[172:175], v[134:137], v[50:65]
	v_add_f32_e32 v200, v200, v94
	v_exp_f32_e32 v103, v103
	v_add_f32_e32 v201, v201, v95
	v_exp_f32_e32 v104, v104
	v_add_f32_e32 v200, v200, v96
	s_waitcnt lgkmcnt(8)
	v_mfma_f32_32x32x16_bf16 v[66:81], v[176:179], v[134:137], v[66:81]
	ds_read2_b64 v[172:175], v242 offset0:8 offset1:10
	ds_read2_b64 v[176:179], v163 offset0:40 offset1:42
	v_exp_f32_e32 v105, v105
	v_add_f32_e32 v201, v201, v97
	v_cvt_pk_bf16_f32 v224, v98, v99
	v_cvt_pk_bf16_f32 v225, v100, v101
	v_cvt_pk_bf16_f32 v226, v102, v103
	s_waitcnt lgkmcnt(3)
	v_mfma_f32_32x32x16_bf16 v[18:33], v[164:167], v[228:231], v[18:33]
	v_cvt_pk_bf16_f32 v227, v104, v105
	v_exp_f32_e32 v106, v106
	v_add_f32_e32 v200, v200, v98
	v_exp_f32_e32 v107, v107
	v_add_f32_e32 v201, v201, v99
	s_waitcnt lgkmcnt(2)
	v_mfma_f32_32x32x16_bf16 v[34:49], v[168:171], v[228:231], v[34:49]
	v_exp_f32_e32 v108, v108
	v_add_f32_e32 v200, v200, v100
	v_exp_f32_e32 v109, v109
	v_add_f32_e32 v201, v201, v101
	v_exp_f32_e32 v110, v110
	s_waitcnt lgkmcnt(9)
	v_mfma_f32_32x32x16_bf16 v[50:65], v[180:183], v[138:141], v[50:65]
	v_add_f32_e32 v200, v200, v102
	v_exp_f32_e32 v111, v111
	v_add_f32_e32 v201, v201, v103
	v_exp_f32_e32 v112, v112
	v_add_f32_e32 v200, v200, v104
	s_waitcnt lgkmcnt(8)
	v_mfma_f32_32x32x16_bf16 v[66:81], v[184:187], v[138:141], v[66:81]
	ds_read2_b64 v[180:183], v242 offset0:12 offset1:14
	ds_read2_b64 v[184:187], v163 offset0:44 offset1:46
	v_exp_f32_e32 v113, v113
	v_add_f32_e32 v201, v201, v105
	v_cvt_pk_bf16_f32 v228, v106, v107
	v_cvt_pk_bf16_f32 v229, v108, v109
	v_cvt_pk_bf16_f32 v230, v110, v111
	s_waitcnt lgkmcnt(3)
	v_mfma_f32_32x32x16_bf16 v[18:33], v[172:175], v[224:227], v[18:33]
	v_cvt_pk_bf16_f32 v231, v112, v113
	v_add_f32_e32 v200, v200, v106
	v_add_f32_e32 v201, v201, v107
	v_add_f32_e32 v200, v200, v108
	v_add_f32_e32 v201, v201, v109
	v_add_f32_e32 v200, v200, v110
	v_add_f32_e32 v201, v201, v111
	v_add_f32_e32 v200, v200, v112
	s_waitcnt lgkmcnt(2)
	v_mfma_f32_32x32x16_bf16 v[34:49], v[176:179], v[224:227], v[34:49]
	v_add_f32_e32 v201, v201, v113
	v_add_f32_e32 v200, v200, v201
	v_add_f32_e32 v162, v162, v200
	s_waitcnt lgkmcnt(9)
	v_mfma_f32_32x32x16_bf16 v[50:65], v[188:191], v[142:145], v[50:65]
	s_waitcnt lgkmcnt(8)
	v_mfma_f32_32x32x16_bf16 v[66:81], v[192:195], v[142:145], v[66:81]
	s_waitcnt lgkmcnt(7)
	v_mfma_f32_32x32x16_bf16 v[50:65], v[196:199], v[146:149], v[50:65]
	s_waitcnt lgkmcnt(6)
	v_mfma_f32_32x32x16_bf16 v[66:81], v[220:223], v[146:149], v[66:81]
	s_waitcnt lgkmcnt(1)
	v_mfma_f32_32x32x16_bf16 v[18:33], v[180:183], v[228:231], v[18:33]
	s_waitcnt lgkmcnt(0)
	v_mfma_f32_32x32x16_bf16 v[34:49], v[184:187], v[228:231], v[34:49]

; #define LAS __attribute__((address_space(3)))
; __device__ __forceinline__ void tr_item(const float* W, int K, int N, bf16_t* WT, LAS float* scr, int item, int lane, int mode, const float* ksc) {
;     const int nblk = N / 32, kb = item / nblk, nb = item % nblk, k0 = 64 * kb, n0 = 32 * nb;
; #pragma unroll 8
;     for (int i = 0; i < 32; ++i) { const int kk = 2 * i + (lane >> 5); float v = W[(size_t)(k0 + kk) * N + n0 + (lane & 31)]; if (ksc) v *= ksc[k0 + kk]; scr[kk * 33 + (lane & 31)] = v; }
.LBB0_997:
	s_mul_hi_i32 s22, s0, 0x2e8ba2e9
	s_lshr_b32 s23, s22, 31
	s_ashr_i32 s22, s22, 5
	s_add_i32 s22, s22, s23
	s_mul_i32 s23, s22, 0xb0
	s_sub_i32 s23, s0, s23
	s_lshl_b32 s24, s22, 6
	s_lshl_b32 s22, s23, 5
	s_ashr_i32 s23, s22, 31
	s_ashr_i32 s25, s24, 31
	v_mov_b32_e32 v25, s25
	v_or_b32_e32 v24, s24, v0
	s_lshl_b64 s[26:27], s[22:23], 2
	v_or_b32_e32 v6, s24, v33
	v_mov_b64_e32 v[26:27], s[26:27]
	v_lshlrev_b64 v[8:9], 2, v[24:25]
	v_or_b32_e32 v10, s24, v34
	v_or_b32_e32 v12, s24, v35
	v_or_b32_e32 v14, s24, v36
	v_or_b32_e32 v16, s24, v37
	v_or_b32_e32 v18, s24, v38
	v_or_b32_e32 v20, s24, v39
	v_ashrrev_i32_e32 v25, 31, v24
	v_mad_i64_i32 v[6:7], s[26:27], v6, s5, v[26:27]
	v_mad_i64_i32 v[10:11], s[26:27], v10, s5, v[26:27]
	v_mad_i64_i32 v[12:13], s[26:27], v12, s5, v[26:27]
	v_mad_i64_i32 v[14:15], s[26:27], v14, s5, v[26:27]
	v_mad_i64_i32 v[16:17], s[26:27], v16, s5, v[26:27]
	v_mad_i64_i32 v[18:19], s[26:27], v18, s5, v[26:27]
	v_mad_i64_i32 v[20:21], s[26:27], v20, s5, v[26:27]
	v_lshlrev_b64 v[22:23], 2, v[24:25]
	v_mad_i64_i32 v[24:25], s[26:27], v24, s5, v[26:27]
	v_lshl_add_u64 v[6:7], v[4:5], 0, v[6:7]
	v_lshl_add_u64 v[10:11], v[4:5], 0, v[10:11]
	v_lshl_add_u64 v[12:13], v[4:5], 0, v[12:13]
	v_lshl_add_u64 v[14:15], v[4:5], 0, v[14:15]
	v_lshl_add_u64 v[16:17], v[4:5], 0, v[16:17]
	v_lshl_add_u64 v[18:19], v[4:5], 0, v[18:19]
	v_lshl_add_u64 v[20:21], v[4:5], 0, v[20:21]
	v_lshl_add_u64 v[24:25], v[4:5], 0, v[24:25]
	s_mov_b64 s[26:27], s[40:41]
	v_mov_b32_e32 v41, v32
	s_mov_b64 s[28:29], 0
	s_and_b64 vcc, exec, s[38:39]
	s_cbranch_vccnz .LBB0_999
; #define LAS __attribute__((address_space(3)))
; #define LDS_WAIT() asm volatile("s_waitcnt lgkmcnt(0)" ::: "memory")
; #define A (*args_opaque((CArgs*)__builtin_amdgcn_kernarg_segment_ptr()))
; __device__ __forceinline__ void tr_item(const float* W, int K, int N, bf16_t* WT, LAS float* scr, int item, int lane, int mode, const float* ksc) {
;     const int nblk = N / 32, kb = item / nblk, nb = item % nblk, k0 = 64 * kb, n0 = 32 * nb;
; #pragma unroll 8
;     for (int i = 0; i < 32; ++i) { const int kk = 2 * i + (lane >> 5); float v = W[(size_t)(k0 + kk) * N + n0 + (lane & 31)]; if (ksc) v *= ksc[k0 + kk]; scr[kk * 33 + (lane & 31)] = v; }
;     LDS_WAIT();
; __device__ __forceinline__ void idle_transposes(ArgsRef A, LAS unsigned char* lds, int lane, int wave, int first_block, int which) {
;     ...
;         for (int it = gw; it < I5; it += NGW) tr_item(A.in[27], 1024, 5632, (bf16_t*)(ws + WS_WUP), scr, it, lane, 3, A.in[26]);
	v_lshl_add_u64 v[112:113], s[40:41], 0, v[8:9]
	global_load_dword v44, v[24:25], off
	global_load_dword v45, v[20:21], off
	global_load_dword v46, v[18:19], off
	global_load_dword v47, v[16:17], off
	global_load_dword v48, v[14:15], off
	global_load_dword v49, v[12:13], off
	global_load_dword v50, v[10:11], off
	global_load_dword v51, v[6:7], off
	global_load_dword v76, v[112:113], off
	global_load_dword v77, v[112:113], off offset:8
	global_load_dword v78, v[112:113], off offset:16
	global_load_dword v79, v[112:113], off offset:24
	global_load_dword v80, v[112:113], off offset:32
	global_load_dword v81, v[112:113], off offset:40
	global_load_dword v82, v[112:113], off offset:48
	global_load_dword v83, v[112:113], off offset:56
	s_mov_b64 s[28:29], 0x58000
	v_lshl_add_u64 v[108:109], v[24:25], 0, s[28:29]
	global_load_dword v52, v[108:109], off
	v_lshl_add_u64 v[110:111], v[20:21], 0, s[28:29]
	global_load_dword v53, v[110:111], off
	v_lshl_add_u64 v[108:109], v[18:19], 0, s[28:29]
	global_load_dword v54, v[108:109], off
	v_lshl_add_u64 v[110:111], v[16:17], 0, s[28:29]
	global_load_dword v55, v[110:111], off
	v_lshl_add_u64 v[108:109], v[14:15], 0, s[28:29]
	global_load_dword v56, v[108:109], off
	v_lshl_add_u64 v[110:111], v[12:13], 0, s[28:29]
	global_load_dword v57, v[110:111], off
	v_lshl_add_u64 v[108:109], v[10:11], 0, s[28:29]
	global_load_dword v58, v[108:109], off
	v_lshl_add_u64 v[110:111], v[6:7], 0, s[28:29]
	global_load_dword v59, v[110:111], off
	global_load_dword v84, v[112:113], off offset:64
	global_load_dword v85, v[112:113], off offset:72
	global_load_dword v86, v[112:113], off offset:80
	global_load_dword v87, v[112:113], off offset:88
	global_load_dword v88, v[112:113], off offset:96
	global_load_dword v89, v[112:113], off offset:104
	global_load_dword v90, v[112:113], off offset:112
	global_load_dword v91, v[112:113], off offset:120
	s_mov_b64 s[28:29], 0xb0000
	v_lshl_add_u64 v[108:109], v[24:25], 0, s[28:29]
	global_load_dword v60, v[108:109], off
	v_lshl_add_u64 v[110:111], v[20:21], 0, s[28:29]
	global_load_dword v61, v[110:111], off
	v_lshl_add_u64 v[108:109], v[18:19], 0, s[28:29]
	global_load_dword v62, v[108:109], off
	v_lshl_add_u64 v[110:111], v[16:17], 0, s[28:29]
	global_load_dword v63, v[110:111], off
	v_lshl_add_u64 v[108:109], v[14:15], 0, s[28:29]
	global_load_dword v64, v[108:109], off
	v_lshl_add_u64 v[110:111], v[12:13], 0, s[28:29]
	global_load_dword v65, v[110:111], off
	v_lshl_add_u64 v[108:109], v[10:11], 0, s[28:29]
	global_load_dword v66, v[108:109], off
	v_lshl_add_u64 v[110:111], v[6:7], 0, s[28:29]
	global_load_dword v67, v[110:111], off
	global_load_dword v92, v[112:113], off offset:128
	global_load_dword v93, v[112:113], off offset:136
	global_load_dword v94, v[112:113], off offset:144
	global_load_dword v95, v[112:113], off offset:152
	global_load_dword v96, v[112:113], off offset:160
	global_load_dword v97, v[112:113], off offset:168
	global_load_dword v98, v[112:113], off offset:176
	global_load_dword v99, v[112:113], off offset:184
	s_waitcnt vmcnt(32)
	v_mul_f32_e32 v44, v44, v76
	v_mul_f32_e32 v45, v45, v77
	v_mul_f32_e32 v46, v46, v78
	v_mul_f32_e32 v47, v47, v79
	v_mul_f32_e32 v48, v48, v80
	v_mul_f32_e32 v49, v49, v81
	v_mul_f32_e32 v50, v50, v82
	v_mul_f32_e32 v51, v51, v83
	ds_write_b32 v32, v44
	ds_write_b32 v32, v45 offset:264
	ds_write_b32 v32, v46 offset:528
	ds_write_b32 v32, v47 offset:792
	ds_write_b32 v32, v48 offset:1056
	ds_write_b32 v32, v49 offset:1320
	ds_write_b32 v32, v50 offset:1584
	ds_write_b32 v32, v51 offset:1848
	s_mov_b64 s[28:29], 0x108000
	v_lshl_add_u64 v[108:109], v[24:25], 0, s[28:29]
	global_load_dword v68, v[108:109], off
	v_lshl_add_u64 v[110:111], v[20:21], 0, s[28:29]
	global_load_dword v69, v[110:111], off
	v_lshl_add_u64 v[108:109], v[18:19], 0, s[28:29]
	global_load_dword v70, v[108:109], off
	v_lshl_add_u64 v[110:111], v[16:17], 0, s[28:29]
	global_load_dword v71, v[110:111], off
	v_lshl_add_u64 v[108:109], v[14:15], 0, s[28:29]
	global_load_dword v72, v[108:109], off
	v_lshl_add_u64 v[110:111], v[12:13], 0, s[28:29]
	global_load_dword v73, v[110:111], off
	v_lshl_add_u64 v[108:109], v[10:11], 0, s[28:29]
	global_load_dword v74, v[108:109], off
	v_lshl_add_u64 v[110:111], v[6:7], 0, s[28:29]
	global_load_dword v75, v[110:111], off
	global_load_dword v100, v[112:113], off offset:192
	global_load_dword v101, v[112:113], off offset:200
	global_load_dword v102, v[112:113], off offset:208
	global_load_dword v103, v[112:113], off offset:216
	global_load_dword v104, v[112:113], off offset:224
	global_load_dword v105, v[112:113], off offset:232
	global_load_dword v106, v[112:113], off offset:240
	global_load_dword v107, v[112:113], off offset:248
	s_waitcnt vmcnt(32)
	v_mul_f32_e32 v52, v52, v84
	v_mul_f32_e32 v53, v53, v85
	v_mul_f32_e32 v54, v54, v86
	v_mul_f32_e32 v55, v55, v87
	v_mul_f32_e32 v56, v56, v88
	v_mul_f32_e32 v57, v57, v89
	v_mul_f32_e32 v58, v58, v90
	v_mul_f32_e32 v59, v59, v91
	ds_write_b32 v32, v52 offset:2112
	ds_write_b32 v32, v53 offset:2376
	ds_write_b32 v32, v54 offset:2640
	ds_write_b32 v32, v55 offset:2904
	ds_write_b32 v32, v56 offset:3168
	ds_write_b32 v32, v57 offset:3432
	ds_write_b32 v32, v58 offset:3696
	ds_write_b32 v32, v59 offset:3960
	s_waitcnt vmcnt(16)
	v_mul_f32_e32 v60, v60, v92
	v_mul_f32_e32 v61, v61, v93
	v_mul_f32_e32 v62, v62, v94
	v_mul_f32_e32 v63, v63, v95
	v_mul_f32_e32 v64, v64, v96
	v_mul_f32_e32 v65, v65, v97
	v_mul_f32_e32 v66, v66, v98
	v_mul_f32_e32 v67, v67, v99
	ds_write_b32 v32, v60 offset:4224
	ds_write_b32 v32, v61 offset:4488
	ds_write_b32 v32, v62 offset:4752
	ds_write_b32 v32, v63 offset:5016
	ds_write_b32 v32, v64 offset:5280
	ds_write_b32 v32, v65 offset:5544
	ds_write_b32 v32, v66 offset:5808
	ds_write_b32 v32, v67 offset:6072
	s_waitcnt vmcnt(0)
	v_mul_f32_e32 v68, v68, v100
	v_mul_f32_e32 v69, v69, v101
	v_mul_f32_e32 v70, v70, v102
	v_mul_f32_e32 v71, v71, v103
	v_mul_f32_e32 v72, v72, v104
	v_mul_f32_e32 v73, v73, v105
	v_mul_f32_e32 v74, v74, v106
	v_mul_f32_e32 v75, v75, v107
	ds_write_b32 v32, v68 offset:6336
	ds_write_b32 v32, v69 offset:6600
	ds_write_b32 v32, v70 offset:6864
	ds_write_b32 v32, v71 offset:7128
	ds_write_b32 v32, v72 offset:7392
	ds_write_b32 v32, v73 offset:7656
	ds_write_b32 v32, v74 offset:7920
	ds_write_b32 v32, v75 offset:8184
	s_branch .LBB0_996
	s_branch .LBB0_999
